# k11 + grid barrier released on the cross-XCD arrival counter itself (all waiters poll it; no separate release word on the path)
# baseline (speedup 1.0000x reference)
.LBB0_465:
	s_or_b64 exec, exec, s[12:13]
	v_cvt_f32_u32_e32 v5, v3
	s_waitcnt vmcnt(0)
	v_readfirstlane_b32 s3, v4
	v_sub_u32_e32 v4, 0, v3
	v_rcp_iflag_f32_e32 v5, v5
	v_add_u32_e32 v6, s3, v2
	v_mul_f32_e32 v5, 0x4f7ffffe, v5
	v_cvt_u32_f32_e32 v5, v5
	v_mul_lo_u32 v2, v4, v5
	v_mul_hi_u32 v2, v5, v2
	v_add_u32_e32 v2, v5, v2
	v_mul_hi_u32 v2, v6, v2
	v_mul_lo_u32 v4, v2, v3
	v_sub_u32_e32 v4, v6, v4
	v_add_u32_e32 v5, 1, v2
	v_cmp_ge_u32_e32 vcc, v4, v3
	s_nop 1
	v_cndmask_b32_e32 v2, v2, v5, vcc
	v_sub_u32_e32 v5, v4, v3
	v_cndmask_b32_e32 v4, v4, v5, vcc
	v_add_u32_e32 v5, 1, v2
	v_cmp_ge_u32_e32 vcc, v4, v3
	v_add_u32_e32 v4, 1, v6
	s_nop 0
	v_cndmask_b32_e32 v2, v2, v5, vcc
	v_mul_lo_u32 v5, v3, v2
	v_add_u32_e32 v3, v5, v3
	v_cmp_ne_u32_e32 vcc, v4, v3
	s_and_saveexec_b64 s[8:9], vcc
	s_xor_b64 s[8:9], exec, s[8:9]
	s_cbranch_execz .LBB0_479
	s_waitcnt lgkmcnt(0)
	v_add_u32_e32 v4, 1, v2
	v_mul_lo_u32 v4, v4, v1
	v_mov_b32_e32 v1, 0x3000
	global_load_dword v1, v1, s[42:43] offset:1024 sc1
	s_add_u32 s14, s42, 0x3400
	s_addc_u32 s15, s43, 0
	s_waitcnt vmcnt(0)
	v_cmp_lt_u32_e32 vcc, v1, v4
	s_and_saveexec_b64 s[12:13], vcc
	s_cbranch_execz .LBB0_478
	s_mov_b32 s3, 1
	s_mov_b64 s[16:17], 0
	v_mov_b32_e32 v1, 0
	s_branch .LBB0_469

.LBB0_471:
	global_load_dword v3, v1, s[14:15] sc1
	s_add_i32 s3, s3, 1
	s_mov_b64 s[22:23], -1
	s_waitcnt vmcnt(0)
	v_cmp_ge_u32_e32 vcc, v3, v4
	s_orn2_b64 s[20:21], vcc, exec
	s_branch .LBB0_468

.LBB0_482:
	s_or_b64 exec, exec, s[12:13]
	v_cvt_f32_u32_e32 v4, v1
	s_waitcnt vmcnt(0)
	v_readfirstlane_b32 s3, v3
	s_add_u32 s12, s42, 0x3500
	s_addc_u32 s13, s43, 0
	v_rcp_iflag_f32_e32 v4, v4
	v_add_u32_e32 v2, s3, v2
	v_add_u32_e32 v5, 1, v2
	s_mov_b64 s[14:15], -1
	v_mul_f32_e32 v3, 0x4f7ffffe, v4
	v_cvt_u32_f32_e32 v3, v3
	v_sub_u32_e32 v4, 0, v1
	v_mul_lo_u32 v4, v4, v3
	v_mul_hi_u32 v4, v3, v4
	v_add_u32_e32 v3, v3, v4
	v_mul_hi_u32 v3, v2, v3
	v_mul_lo_u32 v4, v3, v1
	v_sub_u32_e32 v2, v2, v4
	v_add_u32_e32 v6, 1, v3
	v_cmp_ge_u32_e32 vcc, v2, v1
	v_sub_u32_e32 v4, v2, v1
	s_nop 0
	v_cndmask_b32_e32 v3, v3, v6, vcc
	v_cndmask_b32_e32 v2, v2, v4, vcc
	v_add_u32_e32 v4, 1, v3
	v_cmp_ge_u32_e32 vcc, v2, v1
	s_nop 1
	v_cndmask_b32_e32 v4, v3, v4, vcc
	v_mul_lo_u32 v2, v1, v4
	v_add_u32_e32 v1, v2, v1
	v_mov_b32_e32 v6, v1
	v_cmp_ne_u32_e32 vcc, v5, v1
	v_mov_b64_e32 v[2:3], s[12:13]
	s_and_saveexec_b64 s[8:9], vcc
	s_cbranch_execz .LBB0_494
	v_mov_b32_e32 v1, 0
	global_load_dword v2, v1, s[12:13] offset:-256 sc1
	s_mov_b64 s[18:19], 0
	s_waitcnt vmcnt(0)
	v_cmp_lt_u32_e32 vcc, v2, v6
	s_and_saveexec_b64 s[16:17], vcc
	s_cbranch_execz .LBB0_493
	s_add_u32 s14, s42, 0x200
	s_addc_u32 s15, s43, 0
	s_mov_b32 s3, 1
	s_branch .LBB0_486

.LBB0_488:
	global_load_dword v2, v1, s[12:13] offset:-256 sc1
	s_add_i32 s3, s3, 1
	s_mov_b64 s[22:23], -1
	s_waitcnt vmcnt(0)
	v_cmp_ge_u32_e32 vcc, v2, v6
	s_orn2_b64 s[34:35], vcc, exec
	s_branch .LBB0_485

.LBB0_4158:
	s_or_b64 exec, exec, s[10:11]
	v_cvt_f32_u32_e32 v5, v3
	s_waitcnt vmcnt(0)
	v_readfirstlane_b32 s3, v4
	v_sub_u32_e32 v4, 0, v3
	v_rcp_iflag_f32_e32 v5, v5
	v_add_u32_e32 v6, s3, v2
	v_mul_f32_e32 v5, 0x4f7ffffe, v5
	v_cvt_u32_f32_e32 v5, v5
	v_mul_lo_u32 v2, v4, v5
	v_mul_hi_u32 v2, v5, v2
	v_add_u32_e32 v2, v5, v2
	v_mul_hi_u32 v2, v6, v2
	v_mul_lo_u32 v4, v2, v3
	v_sub_u32_e32 v4, v6, v4
	v_add_u32_e32 v5, 1, v2
	v_cmp_ge_u32_e32 vcc, v4, v3
	s_nop 1
	v_cndmask_b32_e32 v2, v2, v5, vcc
	v_sub_u32_e32 v5, v4, v3
	v_cndmask_b32_e32 v4, v4, v5, vcc
	v_add_u32_e32 v5, 1, v2
	v_cmp_ge_u32_e32 vcc, v4, v3
	v_add_u32_e32 v4, 1, v6
	s_nop 0
	v_cndmask_b32_e32 v2, v2, v5, vcc
	v_mul_lo_u32 v5, v3, v2
	v_add_u32_e32 v3, v5, v3
	v_cmp_ne_u32_e32 vcc, v4, v3
	s_and_saveexec_b64 s[8:9], vcc
	s_xor_b64 s[8:9], exec, s[8:9]
	s_cbranch_execz .LBB0_4172
	s_waitcnt lgkmcnt(0)
	v_add_u32_e32 v4, 1, v2
	v_mul_lo_u32 v4, v4, v1
	v_mov_b32_e32 v1, 0x3000
	global_load_dword v1, v1, s[42:43] offset:1024 sc1
	s_add_u32 s12, s42, 0x3400
	s_addc_u32 s13, s43, 0
	s_waitcnt vmcnt(0)
	v_cmp_lt_u32_e32 vcc, v1, v4
	s_and_saveexec_b64 s[10:11], vcc
	s_cbranch_execz .LBB0_4171
	s_mov_b32 s3, 1
	s_mov_b64 s[14:15], 0
	v_mov_b32_e32 v1, 0
	s_branch .LBB0_4162

.LBB0_4164:
	global_load_dword v3, v1, s[12:13] sc1
	s_add_i32 s3, s3, 1
	s_mov_b64 s[20:21], -1
	s_waitcnt vmcnt(0)
	v_cmp_ge_u32_e32 vcc, v3, v4
	s_orn2_b64 s[18:19], vcc, exec
	s_branch .LBB0_4161

.LBB0_4175:
	s_or_b64 exec, exec, s[10:11]
	v_cvt_f32_u32_e32 v4, v1
	s_waitcnt vmcnt(0)
	v_readfirstlane_b32 s3, v3
	s_add_u32 s10, s42, 0x3500
	s_addc_u32 s11, s43, 0
	v_rcp_iflag_f32_e32 v4, v4
	v_add_u32_e32 v2, s3, v2
	v_add_u32_e32 v5, 1, v2
	s_mov_b64 s[12:13], -1
	v_mul_f32_e32 v3, 0x4f7ffffe, v4
	v_cvt_u32_f32_e32 v3, v3
	v_sub_u32_e32 v4, 0, v1
	v_mul_lo_u32 v4, v4, v3
	v_mul_hi_u32 v4, v3, v4
	v_add_u32_e32 v3, v3, v4
	v_mul_hi_u32 v3, v2, v3
	v_mul_lo_u32 v4, v3, v1
	v_sub_u32_e32 v2, v2, v4
	v_add_u32_e32 v6, 1, v3
	v_cmp_ge_u32_e32 vcc, v2, v1
	v_sub_u32_e32 v4, v2, v1
	s_nop 0
	v_cndmask_b32_e32 v3, v3, v6, vcc
	v_cndmask_b32_e32 v2, v2, v4, vcc
	v_add_u32_e32 v4, 1, v3
	v_cmp_ge_u32_e32 vcc, v2, v1
	s_nop 1
	v_cndmask_b32_e32 v4, v3, v4, vcc
	v_mul_lo_u32 v2, v1, v4
	v_add_u32_e32 v1, v2, v1
	v_mov_b32_e32 v6, v1
	v_cmp_ne_u32_e32 vcc, v5, v1
	v_mov_b64_e32 v[2:3], s[10:11]
	s_and_saveexec_b64 s[8:9], vcc
	s_cbranch_execz .LBB0_4187
	v_mov_b32_e32 v1, 0
	global_load_dword v2, v1, s[10:11] offset:-256 sc1
	s_mov_b64 s[16:17], 0
	s_waitcnt vmcnt(0)
	v_cmp_lt_u32_e32 vcc, v2, v6
	s_and_saveexec_b64 s[14:15], vcc
	s_cbranch_execz .LBB0_4186
	s_add_u32 s12, s42, 0x200
	s_addc_u32 s13, s43, 0
	s_mov_b32 s3, 1
	s_branch .LBB0_4179

.LBB0_4181:
	global_load_dword v2, v1, s[10:11] offset:-256 sc1
	s_add_i32 s3, s3, 1
	s_mov_b64 s[20:21], -1
	s_waitcnt vmcnt(0)
	v_cmp_ge_u32_e32 vcc, v2, v6
	s_orn2_b64 s[26:27], vcc, exec
	s_branch .LBB0_4178
